# v80 + mixers phase QK^T (both sub-blocks) and S=U.G chains: LDS fragment reads run 6 ahead of the MFMAs into dead registers with counted lgkmcnt waits
# speedup vs baseline: 1.0053x; 1.0053x over previous
; #define LAS __attribute__((address_space(3)))
; __device__ __forceinline__ void mixers_phase(Frame& F, const Args& a, int l, const bool do_conv) {
;     ...
;             const int b = unit & 7, n = unit >> 4, kvh = (unit >> 3) & 1;
;             const int rowq0 = b * SEQ + n * 128, rowk0 = rowq0 - 128;
;             const int hq = kvh * 4 + (wave >> 1);
;             u32x4 kv[4], vv[4];
; #pragma unroll
;             for (int i = 0; i < 4; ++i) {
;                 const int v = tid + i * NTHREADS, key = v >> 3, dc = v & 7;
;                 const int rk = (n == 0 && key < 128) ? rowq0 : rowk0 + key;
;                 kv[i] = *(const u32x4*)(Kb + (size_t)rk * 128 + kvh * 64 + dc * 8);
;                 vv[i] = *(const u32x4*)(Vb + (size_t)rk * 128 + kvh * 64 + dc * 8);
;             }
;             bf16x8 qf[2][4];
; #pragma unroll
;             for (int sb = 0; sb < 2; ++sb)
; #pragma unroll
;                 for (int ks = 0; ks < 4; ++ks) qf[sb][ks] = *(const bf16x8*)(Q + (size_t)(rowq0 + (wave & 1) * 64 + sb * 32 + l31) * 512 + hq * 64 + ks * 16 + hi * 8);
;             const float sl = a.in[I_SINK][l * 8 + hq] * LOG2E;
; #pragma unroll
;             for (int i = 0; i < 4; ++i) {
;                 const int v = tid + i * NTHREADS, key = v >> 3, dc = v & 7;
;                 *(LAS u32x4*)(kl + key * AT_KPITCH + dc * 16) = kv[i];
;                 LAS bf16_t* vp = (LAS bf16_t*)(vt + (dc * 8) * AT_VPITCH + key * 2);
;                 vp[0 * (AT_VPITCH / 2)] = (bf16_t)(vv[i].x & 0xffffu); vp[1 * (AT_VPITCH / 2)] = (bf16_t)(vv[i].x >> 16);
;                 vp[2 * (AT_VPITCH / 2)] = (bf16_t)(vv[i].y & 0xffffu); vp[3 * (AT_VPITCH / 2)] = (bf16_t)(vv[i].y >> 16);
;                 vp[4 * (AT_VPITCH / 2)] = (bf16_t)(vv[i].z & 0xffffu); vp[5 * (AT_VPITCH / 2)] = (bf16_t)(vv[i].z >> 16);
;                 vp[6 * (AT_VPITCH / 2)] = (bf16_t)(vv[i].w & 0xffffu); vp[7 * (AT_VPITCH / 2)] = (bf16_t)(vv[i].w >> 16);
;             }
;             __syncthreads();
.LBB0_525:
	s_and_b32 s3, s12, 7
	s_ashr_i32 s6, s12, 4
	s_ashr_i32 s2, s12, 3
	s_lshl_b32 s8, s3, 11
	s_lshl_b32 s0, s6, 7
	s_and_b32 s7, s2, 1
	s_add_i32 s9, s8, s0
	s_add_i32 s14, s9, 0xffffff80
	s_lshl_b32 s15, s7, 2
	s_cmp_lt_u32 s12, 16
	v_readlane_b32 s26, v255, 29
	s_cselect_b64 s[0:1], -1, 0
	v_readlane_b32 s27, v255, 30
	s_and_b64 vcc, s[0:1], s[26:27]
	v_add_u32_e32 v0, s14, v186
	v_mov_b32_e32 v20, s9
	v_cndmask_b32_e32 v2, v0, v20, vcc
	v_readlane_b32 s26, v255, 31
	s_lshl_b32 s72, s7, 7
	v_ashrrev_i32_e32 v3, 31, v2
	v_readlane_b32 s27, v255, 32
	v_lshl_add_u64 v[14:15], v[144:145], 0, s[72:73]
	v_lshl_add_u64 v[18:19], v[146:147], 0, s[72:73]
	v_lshlrev_b64 v[6:7], 8, v[2:3]
	s_and_b64 vcc, s[0:1], s[26:27]
	v_add_u32_e32 v0, s14, v187
	v_lshl_add_u64 v[2:3], v[14:15], 0, v[6:7]
	v_lshl_add_u64 v[28:29], v[18:19], 0, v[6:7]
	v_cndmask_b32_e32 v6, v0, v20, vcc
	v_readlane_b32 s26, v255, 33
	v_ashrrev_i32_e32 v7, 31, v6
	v_readlane_b32 s27, v255, 34
	v_lshlrev_b64 v[10:11], 8, v[6:7]
	s_and_b64 vcc, s[0:1], s[26:27]
	v_add_u32_e32 v0, s14, v188
	v_lshl_add_u64 v[6:7], v[14:15], 0, v[10:11]
	v_lshl_add_u64 v[26:27], v[18:19], 0, v[10:11]
	v_cndmask_b32_e32 v10, v0, v20, vcc
	v_readlane_b32 s26, v255, 35
	v_ashrrev_i32_e32 v11, 31, v10
	v_readlane_b32 s27, v255, 36
	v_lshlrev_b64 v[16:17], 8, v[10:11]
	s_and_b64 vcc, s[0:1], s[26:27]
	v_add_u32_e32 v0, s14, v189
	v_lshl_add_u64 v[10:11], v[14:15], 0, v[16:17]
	v_lshl_add_u64 v[24:25], v[18:19], 0, v[16:17]
	v_cndmask_b32_e32 v16, v0, v20, vcc
	v_readlane_b32 s0, v251, 44
	v_ashrrev_i32_e32 v17, 31, v16
	s_add_i32 s0, s15, s0
	v_or_b32_e32 v30, s9, v177
	v_readlane_b32 s52, v249, 36
	v_lshlrev_b64 v[20:21], 8, v[16:17]
	s_lshl_b32 s72, s0, 7
	v_ashrrev_i32_e32 v31, 31, v30
	v_readlane_b32 s1, v255, 28
	v_readlane_b32 s53, v249, 37
	v_readlane_b32 s54, v249, 38
	v_readlane_b32 s55, v249, 39
	v_readlane_b32 s56, v249, 40
	v_readlane_b32 s57, v249, 41
	v_readlane_b32 s58, v249, 42
	v_readlane_b32 s59, v249, 43
	v_readlane_b32 s60, v249, 44
	v_readlane_b32 s61, v249, 45
	v_readlane_b32 s62, v249, 46
	v_readlane_b32 s63, v249, 47
	v_lshl_add_u64 v[22:23], v[18:19], 0, v[20:21]
	v_lshl_add_u64 v[110:111], v[148:149], 0, s[72:73]
	v_lshlrev_b64 v[18:19], 10, v[30:31]
	v_or_b32_e32 v30, 32, v30
	s_add_i32 s72, s0, s1
	v_readlane_b32 s64, v249, 48
	v_readlane_b32 s65, v249, 49
	v_readlane_b32 s66, v249, 50
	v_readlane_b32 s67, v249, 51
	s_mov_b64 s[52:53], s[56:57]
	v_ashrrev_i32_e32 v31, 31, v30
	s_lshl_b64 s[0:1], s[72:73], 2
	s_mov_b64 s[54:55], s[58:59]
	s_mov_b64 s[56:57], s[60:61]
	v_lshlrev_b64 v[30:31], 10, v[30:31]
	s_add_u32 s0, s56, s0
	v_lshl_add_u64 v[14:15], v[14:15], 0, v[20:21]
	v_lshl_add_u64 v[32:33], v[110:111], 0, v[18:19]
	v_lshl_add_u64 v[30:31], v[110:111], 0, v[30:31]
	s_addc_u32 s1, s57, s1
	global_load_dwordx4 v[2:5], v[2:3], off
	s_cmp_gt_i32 s6, 0
	global_load_dwordx4 v[6:9], v[6:7], off
	s_mov_b64 s[58:59], s[62:63]
	global_load_dwordx4 v[10:13], v[10:11], off
	s_mov_b64 s[60:61], s[64:65]
	global_load_dwordx4 v[14:17], v[14:15], off
	s_nop 0
	global_load_dwordx4 v[18:21], v[32:33], off
	global_load_dwordx4 v[106:109], v[32:33], off offset:32
	global_load_dwordx4 v[102:105], v[32:33], off offset:64
	global_load_dwordx4 v[98:101], v[32:33], off offset:96
	global_load_dwordx4 v[94:97], v[30:31], off
	global_load_dwordx4 v[90:93], v[30:31], off offset:32
	global_load_dwordx4 v[86:89], v[30:31], off offset:64
	global_load_dwordx4 v[82:85], v[30:31], off offset:96
	global_load_dword v112, v1, s[0:1]
	s_nop 0
	global_load_dwordx4 v[28:31], v[28:29], off
	s_nop 0
	global_load_dwordx4 v[32:35], v[26:27], off
	s_nop 0
	global_load_dwordx4 v[24:27], v[24:25], off
	s_nop 0
	global_load_dwordx4 v[36:39], v[22:23], off
	s_cselect_b64 s[0:1], -1, 0
	s_cmp_lt_i32 s6, 1
	s_mov_b64 s[62:63], s[66:67]
	s_waitcnt vmcnt(16)
	ds_write_b128 v191, v[2:5]
	s_waitcnt vmcnt(3)
	ds_write_b16 v192, v28 offset:36864
	ds_write_b16_d16_hi v192, v28 offset:37384
	ds_write_b16 v192, v29 offset:37904
	ds_write_b16_d16_hi v192, v29 offset:38424
	ds_write_b16 v192, v30 offset:38944
	ds_write_b16_d16_hi v192, v30 offset:39464
	ds_write_b16 v192, v31 offset:39984
	ds_write_b16_d16_hi v192, v31 offset:40504
	ds_write_b128 v193, v[6:9]
	s_waitcnt vmcnt(2)
	ds_write_b16 v212, v32 offset:36864
	ds_write_b16_d16_hi v212, v32 offset:37384
	ds_write_b16 v212, v33 offset:37904
	ds_write_b16_d16_hi v212, v33 offset:38424
	ds_write_b16 v212, v34 offset:38944
	ds_write_b16_d16_hi v212, v34 offset:39464
	ds_write_b16 v212, v35 offset:39984
	ds_write_b16_d16_hi v212, v35 offset:40504
	ds_write_b128 v213, v[10:13]
	s_waitcnt vmcnt(1)
	ds_write_b16 v214, v24 offset:36864
	ds_write_b16_d16_hi v214, v24 offset:37384
	ds_write_b16 v214, v25 offset:37904
	ds_write_b16_d16_hi v214, v25 offset:38424
	ds_write_b16 v214, v26 offset:38944
	ds_write_b16_d16_hi v214, v26 offset:39464
	ds_write_b16 v214, v27 offset:39984
	ds_write_b16_d16_hi v214, v27 offset:40504
	ds_write_b128 v215, v[14:17]
	s_waitcnt vmcnt(0)
	ds_write_b16 v216, v36 offset:36864
	ds_write_b16_d16_hi v216, v36 offset:37384
	ds_write_b16 v216, v37 offset:37904
	ds_write_b16_d16_hi v216, v37 offset:38424
	ds_write_b16 v216, v38 offset:38944
	ds_write_b16_d16_hi v216, v38 offset:39464
	ds_write_b16 v216, v39 offset:39984
	ds_write_b16_d16_hi v216, v39 offset:40504
	s_waitcnt lgkmcnt(0)
	s_barrier
; #define LAS __attribute__((address_space(3)))
; __device__ __forceinline__ void mixers_phase(Frame& F, const Args& a, int l, const bool do_conv) {
;     ...
;             for (int sb = 0; sb < 2; ++sb) {
;                 const int q0 = (wave & 1) * 64 + sb * 32;
;                 const size_t qrow = (size_t)(rowq0 + q0 + l31);
;                 f32x16 sc[5];
; #pragma unroll
;                 for (int kt = 0; kt < 5; ++kt) {
;                     f32x16 acc = {};
;                     const LAS unsigned char* kp = kl + (q0 + 32 * kt + l31) * AT_KPITCH + hi * 16;
; #pragma unroll
;                     for (int ks = 0; ks < 4; ++ks) acc = __builtin_amdgcn_mfma_f32_32x32x16_bf16(*(const LAS bf16x8*)(kp + ks * 32), qf[sb][ks], acc, 0, 0, 0);
;                     sc[kt] = acc;
;                 }
	ds_read_b128 v[118:121], v217
	ds_read_b128 v[122:125], v217 offset:32
	ds_read_b128 v[126:129], v217 offset:64
	ds_read_b128 v[130:133], v217 offset:4640
	ds_read_b128 v[134:137], v217 offset:18464
	ds_read_b128 v[138:141], v217 offset:96
	s_waitcnt lgkmcnt(5)
	v_mfma_f32_32x32x16_bf16 v[66:81], v[118:121], v[18:21], 0
	ds_read_b128 v[118:121], v217 offset:4608
	s_waitcnt lgkmcnt(5)
	v_mfma_f32_32x32x16_bf16 v[66:81], v[122:125], v[106:109], v[66:81]
	ds_read_b128 v[122:125], v217 offset:4672
	s_waitcnt lgkmcnt(5)
	v_mfma_f32_32x32x16_bf16 v[66:81], v[126:129], v[102:105], v[66:81]
	ds_read_b128 v[126:129], v217 offset:4704
	s_waitcnt lgkmcnt(3)
	v_mfma_f32_32x32x16_bf16 v[66:81], v[138:141], v[98:101], v[66:81]
	ds_read_b128 v[138:141], v217 offset:9216
	s_waitcnt lgkmcnt(3)
	v_mfma_f32_32x32x16_bf16 v[2:17], v[118:121], v[18:21], 0
	ds_read_b128 v[118:121], v217 offset:9248
	v_mfma_f32_32x32x16_bf16 v[2:17], v[130:133], v[106:109], v[2:17]
	ds_read_b128 v[130:133], v217 offset:9280
	s_waitcnt lgkmcnt(4)
	v_mfma_f32_32x32x16_bf16 v[2:17], v[122:125], v[102:105], v[2:17]
	ds_read_b128 v[122:125], v217 offset:9312
	s_waitcnt lgkmcnt(4)
	v_mfma_f32_32x32x16_bf16 v[2:17], v[126:129], v[98:101], v[2:17]
	ds_read_b128 v[126:129], v217 offset:13824
	s_waitcnt lgkmcnt(4)
	v_mfma_f32_32x32x16_bf16 v[50:65], v[138:141], v[18:21], 0
	ds_read_b128 v[138:141], v217 offset:13856
	s_waitcnt lgkmcnt(4)
	v_mfma_f32_32x32x16_bf16 v[50:65], v[118:121], v[106:109], v[50:65]
	ds_read_b128 v[118:121], v217 offset:13888
	s_waitcnt lgkmcnt(4)
	v_mfma_f32_32x32x16_bf16 v[50:65], v[130:133], v[102:105], v[50:65]
	ds_read_b128 v[130:133], v217 offset:13920
	s_waitcnt lgkmcnt(4)
	v_mfma_f32_32x32x16_bf16 v[50:65], v[122:125], v[98:101], v[50:65]
	ds_read_b128 v[122:125], v217 offset:18432
	s_waitcnt lgkmcnt(4)
	v_mfma_f32_32x32x16_bf16 v[34:49], v[126:129], v[18:21], 0
	ds_read_b128 v[126:129], v217 offset:18496
	s_waitcnt lgkmcnt(4)
	v_mfma_f32_32x32x16_bf16 v[34:49], v[138:141], v[106:109], v[34:49]
	ds_read_b128 v[138:141], v217 offset:18528
	s_waitcnt lgkmcnt(4)
	v_mfma_f32_32x32x16_bf16 v[34:49], v[118:121], v[102:105], v[34:49]
	s_waitcnt lgkmcnt(3)
	v_mfma_f32_32x32x16_bf16 v[34:49], v[130:133], v[98:101], v[34:49]
	s_waitcnt lgkmcnt(2)
	v_mfma_f32_32x32x16_bf16 v[18:33], v[122:125], v[18:21], 0
	v_mfma_f32_32x32x16_bf16 v[18:33], v[134:137], v[106:109], v[18:33]
	s_waitcnt lgkmcnt(1)
	v_mfma_f32_32x32x16_bf16 v[18:33], v[126:129], v[102:105], v[18:33]
	s_waitcnt lgkmcnt(0)
	v_mfma_f32_32x32x16_bf16 v[18:33], v[138:141], v[98:101], v[18:33]
	s_cbranch_scc1 .LBB0_527
	v_readlane_b32 s6, v255, 17
	v_readlane_b32 s7, v255, 18
	s_nop 1
	v_cndmask_b32_e64 v106, v248, v66, s[6:7]
	v_readlane_b32 s6, v255, 19
	v_readlane_b32 s7, v255, 20
	s_nop 1
	v_cndmask_b32_e64 v105, v248, v67, s[6:7]
	v_readlane_b32 s6, v255, 21
	v_readlane_b32 s7, v255, 22
	s_nop 1
	v_cndmask_b32_e64 v104, v248, v68, s[6:7]
	v_readlane_b32 s6, v255, 37
	v_readlane_b32 s7, v255, 38
	s_nop 1
	v_cndmask_b32_e64 v103, v248, v69, s[6:7]
	v_readlane_b32 s6, v255, 39
	v_readlane_b32 s7, v255, 40
	s_nop 1
	v_cndmask_b32_e64 v102, v248, v70, s[6:7]
	v_readlane_b32 s6, v255, 41
	v_readlane_b32 s7, v255, 42
	s_nop 1
	v_cndmask_b32_e64 v101, v248, v71, s[6:7]
	v_readlane_b32 s6, v255, 43
	v_readlane_b32 s7, v255, 44
	s_nop 1
	v_cndmask_b32_e64 v100, v248, v72, s[6:7]
	v_readlane_b32 s6, v255, 45
	v_readlane_b32 s7, v255, 46
	s_nop 1
	v_cndmask_b32_e64 v99, v248, v73, s[6:7]
	v_readlane_b32 s6, v255, 47
	v_readlane_b32 s7, v255, 48
	s_nop 1
	v_cndmask_b32_e64 v74, v248, v74, s[6:7]
	v_readlane_b32 s6, v255, 49
	v_readlane_b32 s7, v255, 50
	s_nop 1
	v_cndmask_b32_e64 v73, v248, v75, s[6:7]
	v_readlane_b32 s6, v255, 51
	v_readlane_b32 s7, v255, 52
	s_nop 1
	v_cndmask_b32_e64 v72, v248, v76, s[6:7]
	v_readlane_b32 s6, v255, 53
	v_readlane_b32 s7, v255, 54
	s_nop 1
	v_cndmask_b32_e64 v71, v248, v77, s[6:7]
	v_readlane_b32 s6, v255, 55
	v_readlane_b32 s7, v255, 56
	s_nop 1
	v_cndmask_b32_e64 v70, v248, v78, s[6:7]
	v_readlane_b32 s6, v255, 57
	v_readlane_b32 s7, v255, 58
	s_nop 1
	v_cndmask_b32_e64 v69, v248, v79, s[6:7]
	v_readlane_b32 s6, v255, 59
	v_readlane_b32 s7, v255, 60
	s_nop 1
	v_cndmask_b32_e64 v68, v248, v80, s[6:7]
	v_readlane_b32 s6, v255, 61
	v_readlane_b32 s7, v255, 62
	s_nop 1
	v_cndmask_b32_e64 v67, v248, v81, s[6:7]
	s_mov_b64 s[6:7], -1
	s_branch .LBB0_528

; __device__ __forceinline__ void mixers_phase(Frame& F, const Args& a, int l, const bool do_conv) {
;     ...
;                 const int dlt = l31 - 4 * hi;
;                 float mx = -1e30f;
; #pragma unroll
;                 for (int kt = 0; kt < 5; ++kt) {
;                     const bool tile_ok = (n > 0) || (q0 + 32 * kt >= 128);
;                     if (!tile_ok) {
; #pragma unroll
;                         for (int r = 0; r < 16; ++r) sc[kt][r] = -1e30f;
;                     } else if (kt == 0 || kt == 4) {
; #pragma unroll
;                         for (int r = 0; r < 16; ++r) {
;                             const int c0 = (r & 3) + 8 * (r >> 2);
;                             const bool ok = (kt == 0) ? (c0 > dlt) : (c0 <= dlt);
;                             sc[kt][r] = ok ? sc[kt][r] : -1e30f;
;                         }
;                     }
; #pragma unroll
;                     for (int r = 0; r < 16; ++r) mx = fmaxf(mx, sc[kt][r]);
;                 }
;                 mx = fmaxf(mx, __shfl_xor(mx, 32));
;                 mx = fmaxf(mx, sl);
.LBB0_528:
	v_or_b32_e32 v98, s9, v176
	v_readlane_b32 s9, v251, 52
	v_readlane_b32 s14, v254, 59
	v_readlane_b32 s15, v254, 60
	v_or_b32_e32 v66, s9, v98
	s_mov_b32 s9, 0xf149f2ca
	v_max3_f32 v75, v106, s9, v105
	v_max3_f32 v75, v75, v104, v103
	v_max3_f32 v75, v75, v102, v101
	v_max3_f32 v75, v75, v100, v99
	v_max3_f32 v75, v75, v74, v73
	v_max3_f32 v75, v75, v72, v71
	v_max3_f32 v75, v75, v70, v69
	v_max3_f32 v75, v75, v68, v67
	v_max3_f32 v75, v75, v2, v3
	v_max3_f32 v75, v75, v4, v5
	v_max3_f32 v75, v75, v6, v7
	v_max3_f32 v75, v75, v8, v9
	v_max3_f32 v75, v75, v10, v11
	v_max3_f32 v75, v75, v12, v13
	v_max3_f32 v75, v75, v14, v15
	v_cndmask_b32_e64 v18, v248, v18, s[14:15]
	v_readlane_b32 s14, v254, 45
	v_max3_f32 v75, v75, v16, v17
	v_cndmask_b32_e64 v51, v248, v51, s[6:7]
	v_cndmask_b32_e64 v50, v248, v50, s[6:7]
	v_readlane_b32 s15, v254, 46
	v_cndmask_b32_e64 v53, v248, v53, s[6:7]
	v_cndmask_b32_e64 v52, v248, v52, s[6:7]
	v_max3_f32 v75, v75, v50, v51
	v_cndmask_b32_e64 v19, v248, v19, s[14:15]
	v_readlane_b32 s14, v255, 3
	v_cndmask_b32_e64 v55, v248, v55, s[6:7]
	v_cndmask_b32_e64 v54, v248, v54, s[6:7]
	v_max3_f32 v75, v75, v52, v53
	v_readlane_b32 s15, v255, 4
	v_cndmask_b32_e64 v57, v248, v57, s[6:7]
	v_cndmask_b32_e64 v56, v248, v56, s[6:7]
	v_max3_f32 v75, v75, v54, v55
	v_cndmask_b32_e64 v20, v248, v20, s[14:15]
	v_readlane_b32 s14, v254, 63
	v_cndmask_b32_e64 v59, v248, v59, s[6:7]
	v_cndmask_b32_e64 v58, v248, v58, s[6:7]
	v_max3_f32 v75, v75, v56, v57
	v_readlane_b32 s15, v255, 0
	v_cndmask_b32_e64 v61, v248, v61, s[6:7]
	v_cndmask_b32_e64 v60, v248, v60, s[6:7]
	v_max3_f32 v75, v75, v58, v59
	v_cndmask_b32_e64 v21, v248, v21, s[14:15]
	v_readlane_b32 s14, v254, 61
	v_cndmask_b32_e64 v63, v248, v63, s[6:7]
	v_cndmask_b32_e64 v62, v248, v62, s[6:7]
	v_max3_f32 v75, v75, v60, v61
	v_readlane_b32 s15, v254, 62
	v_cndmask_b32_e64 v65, v248, v65, s[6:7]
	v_cndmask_b32_e64 v64, v248, v64, s[6:7]
	v_max3_f32 v75, v75, v62, v63
	v_cndmask_b32_e64 v22, v248, v22, s[14:15]
	v_readlane_b32 s14, v255, 13
	v_max3_f32 v75, v75, v64, v65
	v_cndmask_b32_e64 v35, v248, v35, s[6:7]
	v_cndmask_b32_e64 v34, v248, v34, s[6:7]
	v_readlane_b32 s15, v255, 14
	v_cndmask_b32_e64 v37, v248, v37, s[6:7]
	v_cndmask_b32_e64 v36, v248, v36, s[6:7]
	v_max3_f32 v75, v75, v34, v35
	v_cndmask_b32_e64 v23, v248, v23, s[14:15]
	v_readlane_b32 s14, v255, 15
	v_cndmask_b32_e64 v39, v248, v39, s[6:7]
	v_cndmask_b32_e64 v38, v248, v38, s[6:7]
	v_max3_f32 v75, v75, v36, v37
	v_readlane_b32 s15, v255, 16
	v_cndmask_b32_e64 v41, v248, v41, s[6:7]
	v_cndmask_b32_e64 v40, v248, v40, s[6:7]
	v_max3_f32 v75, v75, v38, v39
	v_cndmask_b32_e64 v24, v248, v24, s[14:15]
	v_readlane_b32 s14, v255, 1
	v_cndmask_b32_e64 v43, v248, v43, s[6:7]
	v_cndmask_b32_e64 v42, v248, v42, s[6:7]
	v_max3_f32 v75, v75, v40, v41
	v_readlane_b32 s15, v255, 2
	v_cndmask_b32_e64 v45, v248, v45, s[6:7]
	v_cndmask_b32_e64 v44, v248, v44, s[6:7]
	v_max3_f32 v75, v75, v42, v43
	v_cndmask_b32_e64 v25, v248, v25, s[14:15]
	v_readlane_b32 s14, v255, 5
	v_cndmask_b32_e64 v47, v248, v47, s[6:7]
	v_cndmask_b32_e64 v46, v248, v46, s[6:7]
	v_max3_f32 v75, v75, v44, v45
	v_readlane_b32 s15, v255, 6
	v_cndmask_b32_e64 v49, v248, v49, s[6:7]
	v_cndmask_b32_e64 v48, v248, v48, s[6:7]
	v_max3_f32 v75, v75, v46, v47
	v_cndmask_b32_e64 v26, v248, v26, s[14:15]
	v_readlane_b32 s14, v255, 7
	v_max3_f32 v75, v75, v48, v49
	v_readlane_b32 s15, v255, 8
	v_max3_f32 v75, v75, v18, v19
	v_max3_f32 v75, v75, v20, v21
	v_cndmask_b32_e64 v27, v248, v27, s[14:15]
	v_readlane_b32 s14, v255, 9
	v_readlane_b32 s15, v255, 10
	v_max3_f32 v75, v75, v22, v23
	v_max3_f32 v75, v75, v24, v25
	v_cndmask_b32_e64 v28, v248, v28, s[14:15]
	v_readlane_b32 s14, v255, 11
	v_readlane_b32 s15, v255, 12
	v_max3_f32 v75, v75, v26, v27
	v_cndmask_b32_e64 v30, v248, v30, s[18:19]
	v_cndmask_b32_e64 v29, v248, v29, s[14:15]
	v_cndmask_b32_e64 v31, v248, v31, s[20:21]
	v_max3_f32 v75, v75, v28, v29
	v_cndmask_b32_e64 v32, v248, v32, s[22:23]
	v_cndmask_b32_e64 v33, v248, v33, s[24:25]
	v_max3_f32 v75, v75, v30, v31
	v_max3_f32 v75, v75, v32, v33
	ds_bpermute_b32 v76, v178, v75
	v_mul_f32_e32 v0, 0x3fb8aa3b, v112
	s_mov_b32 s9, 0x3fb8aa3b
	s_mov_b32 s17, s73
	s_andn2_b64 vcc, exec, s[0:1]
	s_waitcnt lgkmcnt(0)
; __device__ __forceinline__ void mixers_phase(Frame& F, const Args& a, int l, const bool do_conv) {
;     ...
;                 float ls = 0.f;
; #pragma unroll
;                 for (int kt = 0; kt < 5; ++kt)
; #pragma unroll
;                     for (int r = 0; r < 16; ++r) { const float p = __builtin_amdgcn_exp2f(sc[kt][r] - mx); sc[kt][r] = p; ls += p; }
	v_max3_f32 v129, v75, v76, v0
	v_sub_f32_e32 v75, v106, v129
	v_exp_f32_e32 v130, v75
	v_sub_f32_e32 v76, v105, v129
	v_exp_f32_e32 v131, v76
	v_sub_f32_e32 v76, v104, v129
	v_exp_f32_e32 v132, v76
	v_sub_f32_e32 v76, v103, v129
	v_exp_f32_e32 v133, v76
	v_sub_f32_e32 v76, v102, v129
	v_add_f32_e32 v75, 0, v130
	v_exp_f32_e32 v134, v76
	v_sub_f32_e32 v76, v101, v129
	v_add_f32_e32 v75, v131, v75
	v_exp_f32_e32 v135, v76
	v_sub_f32_e32 v76, v100, v129
	v_add_f32_e32 v75, v132, v75
	v_exp_f32_e32 v136, v76
	v_sub_f32_e32 v76, v99, v129
	v_add_f32_e32 v75, v133, v75
	v_exp_f32_e32 v137, v76
	v_sub_f32_e32 v74, v74, v129
	v_add_f32_e32 v75, v134, v75
	v_exp_f32_e32 v81, v74
	v_sub_f32_e32 v73, v73, v129
	v_add_f32_e32 v75, v135, v75
	v_exp_f32_e32 v100, v73
	v_sub_f32_e32 v72, v72, v129
	v_add_f32_e32 v75, v136, v75
	v_exp_f32_e32 v102, v72
	v_sub_f32_e32 v71, v71, v129
	v_add_f32_e32 v75, v137, v75
	v_exp_f32_e32 v105, v71
	v_sub_f32_e32 v70, v70, v129
	v_add_f32_e32 v74, v81, v75
	v_exp_f32_e32 v109, v70
	v_sub_f32_e32 v69, v69, v129
	v_add_f32_e32 v73, v100, v74
	v_exp_f32_e32 v114, v69
	v_sub_f32_e32 v68, v68, v129
	v_add_f32_e32 v72, v102, v73
	v_exp_f32_e32 v116, v68
	v_sub_f32_e32 v67, v67, v129
	v_add_f32_e32 v71, v105, v72
	v_exp_f32_e32 v119, v67
	v_sub_f32_e32 v2, v2, v129
	v_add_f32_e32 v70, v109, v71
	v_exp_f32_e32 v117, v2
	v_sub_f32_e32 v3, v3, v129
	v_add_f32_e32 v69, v114, v70
	v_exp_f32_e32 v121, v3
	v_sub_f32_e32 v3, v4, v129
	v_add_f32_e32 v68, v116, v69
	v_exp_f32_e32 v123, v3
	v_sub_f32_e32 v3, v5, v129
	v_add_f32_e32 v67, v119, v68
	v_exp_f32_e32 v124, v3
	v_sub_f32_e32 v3, v6, v129
	v_add_f32_e32 v2, v117, v67
	v_exp_f32_e32 v125, v3
	v_sub_f32_e32 v3, v7, v129
	v_add_f32_e32 v2, v121, v2
	v_exp_f32_e32 v126, v3
	v_sub_f32_e32 v3, v8, v129
	v_add_f32_e32 v2, v123, v2
	v_exp_f32_e32 v127, v3
	v_sub_f32_e32 v3, v9, v129
	v_add_f32_e32 v2, v124, v2
	v_exp_f32_e32 v128, v3
	v_sub_f32_e32 v3, v10, v129
	v_add_f32_e32 v2, v125, v2
	v_exp_f32_e32 v104, v3
	v_sub_f32_e32 v3, v11, v129
	v_add_f32_e32 v2, v126, v2
	v_exp_f32_e32 v107, v3
	v_sub_f32_e32 v3, v12, v129
	v_add_f32_e32 v2, v127, v2
	v_exp_f32_e32 v108, v3
	v_sub_f32_e32 v3, v13, v129
	v_add_f32_e32 v2, v128, v2
	v_exp_f32_e32 v113, v3
	v_sub_f32_e32 v3, v14, v129
	v_add_f32_e32 v2, v104, v2
	v_exp_f32_e32 v115, v3
	v_sub_f32_e32 v3, v15, v129
	v_add_f32_e32 v2, v107, v2
	v_exp_f32_e32 v118, v3
	v_sub_f32_e32 v3, v16, v129
	v_add_f32_e32 v2, v108, v2
	v_exp_f32_e32 v120, v3
	v_sub_f32_e32 v3, v17, v129
	v_add_f32_e32 v2, v113, v2
	v_exp_f32_e32 v122, v3
	v_sub_f32_e32 v3, v50, v129
	v_add_f32_e32 v2, v115, v2
	v_exp_f32_e32 v77, v3
	v_sub_f32_e32 v3, v51, v129
	v_add_f32_e32 v2, v118, v2
	v_exp_f32_e32 v78, v3
	v_sub_f32_e32 v3, v52, v129
	v_add_f32_e32 v2, v120, v2
	v_exp_f32_e32 v79, v3
	v_sub_f32_e32 v3, v53, v129
	v_add_f32_e32 v2, v122, v2
	v_exp_f32_e32 v80, v3
	v_sub_f32_e32 v3, v54, v129
	v_add_f32_e32 v2, v77, v2
	v_exp_f32_e32 v99, v3
	v_sub_f32_e32 v3, v55, v129
	v_add_f32_e32 v2, v78, v2
	v_exp_f32_e32 v101, v3
	v_sub_f32_e32 v3, v56, v129
	v_add_f32_e32 v2, v79, v2
	v_exp_f32_e32 v103, v3
	v_sub_f32_e32 v3, v57, v129
	v_add_f32_e32 v2, v80, v2
	v_exp_f32_e32 v106, v3
	v_sub_f32_e32 v3, v58, v129
	v_add_f32_e32 v2, v99, v2
	v_exp_f32_e32 v69, v3
	v_sub_f32_e32 v3, v59, v129
	v_add_f32_e32 v2, v101, v2
	v_exp_f32_e32 v70, v3
	v_sub_f32_e32 v3, v60, v129
	v_add_f32_e32 v2, v103, v2
	v_exp_f32_e32 v71, v3
	v_sub_f32_e32 v3, v61, v129
	v_add_f32_e32 v2, v106, v2
	v_exp_f32_e32 v72, v3
	v_sub_f32_e32 v3, v62, v129
	v_add_f32_e32 v2, v69, v2
	v_exp_f32_e32 v73, v3
	v_sub_f32_e32 v3, v63, v129
	v_add_f32_e32 v2, v70, v2
	v_exp_f32_e32 v74, v3
	v_sub_f32_e32 v3, v64, v129
	v_add_f32_e32 v2, v71, v2
	v_exp_f32_e32 v75, v3
	v_sub_f32_e32 v3, v65, v129
	v_add_f32_e32 v2, v72, v2
	v_exp_f32_e32 v76, v3
	v_sub_f32_e32 v3, v34, v129
	v_add_f32_e32 v2, v73, v2
	v_exp_f32_e32 v60, v3
	v_sub_f32_e32 v3, v35, v129
	v_add_f32_e32 v2, v74, v2
	v_exp_f32_e32 v61, v3
	v_sub_f32_e32 v3, v36, v129
	v_add_f32_e32 v2, v75, v2
	v_exp_f32_e32 v62, v3
	v_sub_f32_e32 v3, v37, v129
	v_add_f32_e32 v2, v76, v2
	v_exp_f32_e32 v63, v3
	v_sub_f32_e32 v3, v38, v129
	v_add_f32_e32 v2, v60, v2
	v_exp_f32_e32 v64, v3
	v_sub_f32_e32 v3, v39, v129
	v_add_f32_e32 v2, v61, v2
	v_exp_f32_e32 v65, v3
	v_sub_f32_e32 v3, v40, v129
	v_add_f32_e32 v2, v62, v2
	v_exp_f32_e32 v67, v3
	v_sub_f32_e32 v3, v41, v129
	v_add_f32_e32 v2, v63, v2
	v_exp_f32_e32 v68, v3
	v_sub_f32_e32 v3, v42, v129
	v_add_f32_e32 v2, v64, v2
	v_exp_f32_e32 v52, v3
	v_sub_f32_e32 v3, v43, v129
	v_add_f32_e32 v2, v65, v2
	v_exp_f32_e32 v53, v3
	v_sub_f32_e32 v3, v44, v129
	v_add_f32_e32 v2, v67, v2
	v_exp_f32_e32 v54, v3
	v_sub_f32_e32 v3, v45, v129
	v_add_f32_e32 v2, v68, v2
	v_exp_f32_e32 v55, v3
	v_sub_f32_e32 v3, v46, v129
	v_add_f32_e32 v2, v52, v2
	v_exp_f32_e32 v56, v3
	v_sub_f32_e32 v3, v47, v129
	v_add_f32_e32 v2, v53, v2
	v_exp_f32_e32 v57, v3
	v_sub_f32_e32 v3, v48, v129
	v_add_f32_e32 v2, v54, v2
	v_exp_f32_e32 v58, v3
	v_sub_f32_e32 v3, v49, v129
	v_add_f32_e32 v2, v55, v2
	v_exp_f32_e32 v59, v3
	v_sub_f32_e32 v3, v18, v129
	v_add_f32_e32 v2, v56, v2
	v_exp_f32_e32 v44, v3
	v_sub_f32_e32 v3, v19, v129
	v_add_f32_e32 v2, v57, v2
	v_exp_f32_e32 v45, v3
	v_sub_f32_e32 v3, v20, v129
	v_add_f32_e32 v2, v58, v2
	v_exp_f32_e32 v46, v3
	v_sub_f32_e32 v3, v21, v129
	v_add_f32_e32 v2, v59, v2
	v_exp_f32_e32 v47, v3
	v_sub_f32_e32 v3, v22, v129
	v_add_f32_e32 v2, v44, v2
	v_exp_f32_e32 v48, v3
	v_sub_f32_e32 v3, v23, v129
	v_add_f32_e32 v2, v45, v2
	v_exp_f32_e32 v49, v3
	v_sub_f32_e32 v3, v24, v129
	v_add_f32_e32 v2, v46, v2
; #define LAS __attribute__((address_space(3)))
; __device__ __forceinline__ unsigned pk2(float lo, float hi) { const f32x2 v = {lo, hi}; const bf16x2_hw b = __builtin_convertvector(v, bf16x2_hw); return __builtin_bit_cast(unsigned, b); }
; __device__ __forceinline__ float xsum32p(float x) { const unsigned u = __builtin_bit_cast(unsigned, x); const auto r = __builtin_amdgcn_permlane32_swap(u, u ^ 0x80000000u, false, false); unsigned r0 = r[0], r1 = r[1]; asm("" : "+v"(r0), "+v"(r1)); return fabsf(__builtin_bit_cast(float, r0) + __builtin_bit_cast(float, r1)); }
; __device__ __forceinline__ void mixers_phase(Frame& F, const Args& a, int l, const bool do_conv) {
;     ...
;                 ls = xsum32p(ls);
;                 ls += __builtin_amdgcn_exp2f(sl - mx);
;                 f32x16 o0 = {}, o1 = {};
; #pragma unroll
;                 for (int kt = 0; kt < 5; ++kt)
; #pragma unroll
;                     for (int s2 = 0; s2 < 2; ++s2) {
;                         u32x4 pw; pw.x = pk2(sc[kt][8 * s2 + 0], sc[kt][8 * s2 + 1]); pw.y = pk2(sc[kt][8 * s2 + 2], sc[kt][8 * s2 + 3]); pw.z = pk2(sc[kt][8 * s2 + 4], sc[kt][8 * s2 + 5]); pw.w = pk2(sc[kt][8 * s2 + 6], sc[kt][8 * s2 + 7]);
;                         const bf16x8 pf = __builtin_bit_cast(bf16x8, pw);
;                         const int col = q0 + 32 * kt + 16 * s2 + 4 * hi;
;                         const LAS unsigned char* vp0 = vt + l31 * AT_VPITCH + col * 2;
;                         const LAS unsigned char* vp1 = vp0 + 32 * AT_VPITCH;
;                         const u32x2 a0 = *(const LAS u32x2*)(vp0), a1 = *(const LAS u32x2*)(vp0 + 16);
;                         const u32x2 c0 = *(const LAS u32x2*)(vp1), c1 = *(const LAS u32x2*)(vp1 + 16);
;                         u32x4 va; va.x = a0.x; va.y = a0.y; va.z = a1.x; va.w = a1.y;
;                         u32x4 vc; vc.x = c0.x; vc.y = c0.y; vc.z = c1.x; vc.w = c1.y;
;                         o0 = __builtin_amdgcn_mfma_f32_32x32x16_bf16(__builtin_bit_cast(bf16x8, va), pf, o0, 0, 0, 0);
;                         o1 = __builtin_amdgcn_mfma_f32_32x32x16_bf16(__builtin_bit_cast(bf16x8, vc), pf, o1, 0, 0, 0);
;                     }
	v_exp_f32_e32 v50, v3
	v_sub_f32_e32 v3, v25, v129
	v_add_f32_e32 v2, v47, v2
	v_exp_f32_e32 v51, v3
	v_sub_f32_e32 v3, v26, v129
	v_add_f32_e32 v2, v48, v2
	v_exp_f32_e32 v36, v3
	v_sub_f32_e32 v3, v27, v129
	v_add_f32_e32 v2, v49, v2
	v_exp_f32_e32 v37, v3
	v_sub_f32_e32 v3, v28, v129
	v_add_f32_e32 v2, v50, v2
	v_exp_f32_e32 v38, v3
	v_sub_f32_e32 v3, v29, v129
	v_add_f32_e32 v2, v51, v2
	v_exp_f32_e32 v39, v3
	v_sub_f32_e32 v3, v30, v129
	v_add_f32_e32 v2, v36, v2
	v_exp_f32_e32 v40, v3
	v_sub_f32_e32 v3, v31, v129
	v_add_f32_e32 v2, v37, v2
	v_exp_f32_e32 v41, v3
	v_sub_f32_e32 v3, v32, v129
	v_add_f32_e32 v2, v38, v2
	v_exp_f32_e32 v42, v3
	v_sub_f32_e32 v3, v33, v129
	v_add_f32_e32 v2, v39, v2
	v_exp_f32_e32 v43, v3
	v_add_f32_e32 v2, v40, v2
	v_add_f32_e32 v2, v41, v2
	v_add_f32_e32 v2, v42, v2
	v_add_f32_e32 v2, v43, v2
	v_xor_b32_e32 v3, 0x80000000, v2
	s_nop 1
	v_permlane32_swap_b32_e32 v2, v3
	v_cvt_pk_bf16_f32 v18, v130, v131
	v_add_f32_e32 v34, v2, v3
	v_fma_f32 v2, v112, s9, -v129
	v_add_u32_e32 v112, 0x9000, v218
	v_add_u32_e32 v129, 0xd000, v218
	v_exp_f32_e32 v35, v2
	v_cvt_pk_bf16_f32 v19, v132, v133
	ds_read2_b64 v[2:5], v112 offset1:2
	ds_read2_b64 v[130:133], v112 offset0:4 offset1:6
	ds_read2_b64 v[22:25], v129 offset0:32 offset1:34
	v_cvt_pk_bf16_f32 v20, v134, v135
	v_cvt_pk_bf16_f32 v21, v136, v137
	ds_read2_b64 v[138:141], v129 offset0:36 offset1:38
	v_cvt_pk_bf16_f32 v134, v81, v100
	s_waitcnt lgkmcnt(3)
	v_mfma_f32_32x32x16_bf16 v[2:17], v[2:5], v[18:21], 0
	v_cvt_pk_bf16_f32 v135, v102, v105
	v_cvt_pk_bf16_f32 v136, v109, v114
	v_cvt_pk_bf16_f32 v137, v116, v119
	v_cvt_pk_bf16_f32 v119, v120, v122
	v_cvt_pk_bf16_f32 v116, v104, v107
	v_cvt_pk_bf16_f32 v118, v115, v118
	v_cvt_pk_bf16_f32 v79, v79, v80
	s_waitcnt lgkmcnt(1)
	v_mfma_f32_32x32x16_bf16 v[18:33], v[22:25], v[18:21], 0
	v_cvt_pk_bf16_f32 v80, v99, v101
	v_cvt_pk_bf16_f32 v81, v103, v106
	v_cvt_pk_bf16_f32 v78, v77, v78
	v_cvt_pk_bf16_f32 v71, v71, v72
	v_cvt_pk_bf16_f32 v72, v73, v74
	v_cvt_pk_bf16_f32 v73, v75, v76
	v_cvt_pk_bf16_f32 v70, v69, v70
	v_mfma_f32_32x32x16_bf16 v[2:17], v[130:133], v[134:137], v[2:17]
	v_cvt_pk_bf16_f32 v131, v123, v124
	v_cvt_pk_bf16_f32 v132, v125, v126
	v_cvt_pk_bf16_f32 v133, v127, v128
	v_cvt_pk_bf16_f32 v130, v117, v121
	v_cvt_pk_bf16_f32 v117, v108, v113
	v_cvt_pk_bf16_f32 v60, v60, v61
	v_cvt_pk_bf16_f32 v61, v62, v63
	s_waitcnt lgkmcnt(0)
	v_mfma_f32_32x32x16_bf16 v[18:33], v[138:141], v[134:137], v[18:33]
	ds_read2_b64 v[124:127], v112 offset0:8 offset1:10
	ds_read2_b64 v[134:137], v129 offset0:40 offset1:42
	v_cvt_pk_bf16_f32 v63, v67, v68
	v_cvt_pk_bf16_f32 v62, v64, v65
	v_cvt_pk_bf16_f32 v52, v52, v53
	v_cvt_pk_bf16_f32 v53, v54, v55
	v_cvt_pk_bf16_f32 v54, v56, v57
	v_cvt_pk_bf16_f32 v55, v58, v59
	s_waitcnt lgkmcnt(1)
	v_mfma_f32_32x32x16_bf16 v[2:17], v[124:127], v[130:133], v[2:17]
	ds_read2_b64 v[120:123], v112 offset0:12 offset1:14
	ds_read2_b64 v[124:127], v129 offset0:44 offset1:46
	ds_read2_b64 v[100:103], v112 offset0:16 offset1:18
	ds_read2_b64 v[104:107], v129 offset0:48 offset1:50
	v_cvt_pk_bf16_f32 v44, v44, v45
	v_cvt_pk_bf16_f32 v45, v46, v47
	v_cvt_pk_bf16_f32 v46, v48, v49
	v_cvt_pk_bf16_f32 v47, v50, v51
	v_cvt_pk_bf16_f32 v36, v36, v37
	s_waitcnt lgkmcnt(4)
	v_mfma_f32_32x32x16_bf16 v[18:33], v[134:137], v[130:133], v[18:33]
	v_cvt_pk_bf16_f32 v37, v38, v39
	v_cvt_pk_bf16_f32 v38, v40, v41
	v_cvt_pk_bf16_f32 v39, v42, v43
	v_add_f32_e64 v34, |v34|, v35
	v_rcp_f32_e32 v34, v34
	v_ashrrev_i32_e32 v67, 31, v66
	s_waitcnt lgkmcnt(3)
	v_mfma_f32_32x32x16_bf16 v[2:17], v[120:123], v[116:119], v[2:17]
	s_waitcnt lgkmcnt(2)
	v_mfma_f32_32x32x16_bf16 v[18:33], v[124:127], v[116:119], v[18:33]
	s_waitcnt lgkmcnt(1)
	v_mfma_f32_32x32x16_bf16 v[2:17], v[100:103], v[78:81], v[2:17]
	s_waitcnt lgkmcnt(0)
	v_mfma_f32_32x32x16_bf16 v[18:33], v[104:107], v[78:81], v[18:33]
	ds_read2_b64 v[74:77], v112 offset0:20 offset1:22
	ds_read2_b64 v[78:81], v129 offset0:52 offset1:54
	s_waitcnt lgkmcnt(1)
	v_mfma_f32_32x32x16_bf16 v[2:17], v[74:77], v[70:73], v[2:17]
	s_waitcnt lgkmcnt(0)
	v_mfma_f32_32x32x16_bf16 v[18:33], v[78:81], v[70:73], v[18:33]
	ds_read2_b64 v[68:71], v112 offset0:24 offset1:26
	ds_read2_b64 v[72:75], v129 offset0:56 offset1:58
	s_waitcnt lgkmcnt(1)
	v_mfma_f32_32x32x16_bf16 v[2:17], v[68:71], v[60:63], v[2:17]
	s_waitcnt lgkmcnt(0)
	v_mfma_f32_32x32x16_bf16 v[18:33], v[72:75], v[60:63], v[18:33]
	ds_read2_b64 v[56:59], v112 offset0:28 offset1:30
	ds_read2_b64 v[60:63], v129 offset0:60 offset1:62
	s_waitcnt lgkmcnt(1)
	v_mfma_f32_32x32x16_bf16 v[2:17], v[56:59], v[52:55], v[2:17]
	s_waitcnt lgkmcnt(0)
	v_mfma_f32_32x32x16_bf16 v[18:33], v[60:63], v[52:55], v[18:33]
	ds_read2_b64 v[48:51], v112 offset0:32 offset1:34
	ds_read2_b64 v[52:55], v129 offset0:64 offset1:66
	s_waitcnt lgkmcnt(1)
	v_mfma_f32_32x32x16_bf16 v[2:17], v[48:51], v[44:47], v[2:17]
	s_waitcnt lgkmcnt(0)
	v_mfma_f32_32x32x16_bf16 v[18:33], v[52:55], v[44:47], v[18:33]
	ds_read2_b64 v[40:43], v112 offset0:36 offset1:38
	ds_read2_b64 v[44:47], v129 offset0:68 offset1:70
	s_waitcnt lgkmcnt(1)
	v_mfma_f32_32x32x16_bf16 v[2:17], v[40:43], v[36:39], v[2:17]
	s_waitcnt lgkmcnt(0)
; #define LAS __attribute__((address_space(3)))
; __device__ __forceinline__ unsigned pk2(float lo, float hi) { const f32x2 v = {lo, hi}; const bf16x2_hw b = __builtin_convertvector(v, bf16x2_hw); return __builtin_bit_cast(unsigned, b); }
; __device__ __forceinline__ void mixers_phase(Frame& F, const Args& a, int l, const bool do_conv) {
;     ...
;             for (int sb = 0; sb < 2; ++sb) {
;                 const int q0 = (wave & 1) * 64 + sb * 32;
;                 const size_t qrow = (size_t)(rowq0 + q0 + l31);
;                 f32x16 sc[5];
; #pragma unroll
;                 for (int kt = 0; kt < 5; ++kt) {
;                     f32x16 acc = {};
;                     const LAS unsigned char* kp = kl + (q0 + 32 * kt + l31) * AT_KPITCH + hi * 16;
; #pragma unroll
;                     for (int ks = 0; ks < 4; ++ks) acc = __builtin_amdgcn_mfma_f32_32x32x16_bf16(*(const LAS bf16x8*)(kp + ks * 32), qf[sb][ks], acc, 0, 0, 0);
;                     sc[kt] = acc;
;                 }
;     ...
;                 const float inv = __builtin_amdgcn_rcpf(ls);
;                 bf16_t* op = AO + qrow * 512 + hq * 64 + 8 * hi;
; #pragma unroll
;                 for (int hh = 0; hh < 2; ++hh) {
;                     unsigned wx[4], wy[4];
; #pragma unroll
;                     for (int qd = 0; qd < 4; ++qd) {
;                         float y0, y1, y2, y3;
;                         if (hh == 0) { y0 = o0[4 * qd]; y1 = o0[4 * qd + 1]; y2 = o0[4 * qd + 2]; y3 = o0[4 * qd + 3]; } else { y0 = o1[4 * qd]; y1 = o1[4 * qd + 1]; y2 = o1[4 * qd + 2]; y3 = o1[4 * qd + 3]; }
;                         wx[qd] = pk2(y0 * inv, y1 * inv); wy[qd] = pk2(y2 * inv, y3 * inv);
;                     }
;                     const auto a0x = __builtin_amdgcn_permlane32_swap(wx[0], wx[1], false, false), a0y = __builtin_amdgcn_permlane32_swap(wy[0], wy[1], false, false);
;                     const auto a1x = __builtin_amdgcn_permlane32_swap(wx[2], wx[3], false, false), a1y = __builtin_amdgcn_permlane32_swap(wy[2], wy[3], false, false);
;                     u32x4 lo4, hi4; lo4.x = a0x[0]; lo4.y = a0y[0]; lo4.z = a0x[1]; lo4.w = a0y[1]; hi4.x = a1x[0]; hi4.y = a1y[0]; hi4.z = a1x[1]; hi4.w = a1y[1];
;                     *(u32x4*)(op + 32 * hh) = lo4; *(u32x4*)(op + 32 * hh + 16) = hi4;
;                 }
	v_mfma_f32_32x32x16_bf16 v[18:33], v[44:47], v[36:39], v[18:33]
	s_nop 9
	v_mul_f32_e64 v2, v2, v34
	v_mul_f32_e64 v3, v3, v34
	v_mul_f32_e64 v4, v4, v34
	v_mul_f32_e64 v5, v5, v34
	v_cvt_pk_bf16_f32 v2, v2, v3
	v_cvt_pk_bf16_f32 v3, v4, v5
	v_pk_mul_f32 v[4:5], v[6:7], v[34:35] op_sel_hi:[1,0]
	v_pk_mul_f32 v[6:7], v[8:9], v[34:35] op_sel_hi:[1,0]
	v_cvt_pk_bf16_f32 v4, v4, v5
	v_cvt_pk_bf16_f32 v5, v6, v7
	v_pk_mul_f32 v[6:7], v[10:11], v[34:35] op_sel_hi:[1,0]
	v_pk_mul_f32 v[8:9], v[12:13], v[34:35] op_sel_hi:[1,0]
	v_lshlrev_b64 v[36:37], 10, v[66:67]
	v_cvt_pk_bf16_f32 v6, v6, v7
	v_cvt_pk_bf16_f32 v7, v8, v9
	v_pk_mul_f32 v[8:9], v[14:15], v[34:35] op_sel_hi:[1,0]
	v_pk_mul_f32 v[10:11], v[16:17], v[34:35] op_sel_hi:[1,0]
	v_lshl_add_u64 v[36:37], v[110:111], 0, v[36:37]
	v_cvt_pk_bf16_f32 v8, v8, v9
	v_cvt_pk_bf16_f32 v9, v10, v11
	v_permlane32_swap_b32_e32 v2, v4
	v_permlane32_swap_b32_e32 v3, v5
	v_permlane32_swap_b32_e32 v6, v8
	v_permlane32_swap_b32_e32 v7, v9
	global_store_dwordx4 v[36:37], v[2:5], off
	global_store_dwordx4 v[36:37], v[6:9], off offset:32
	v_pk_mul_f32 v[10:11], v[32:33], v[34:35] op_sel_hi:[1,0]
	v_pk_mul_f32 v[2:3], v[18:19], v[34:35] op_sel_hi:[1,0]
	v_pk_mul_f32 v[4:5], v[20:21], v[34:35] op_sel_hi:[1,0]
	v_cvt_pk_bf16_f32 v2, v2, v3
	v_cvt_pk_bf16_f32 v3, v4, v5
	v_pk_mul_f32 v[4:5], v[22:23], v[34:35] op_sel_hi:[1,0]
	v_pk_mul_f32 v[6:7], v[24:25], v[34:35] op_sel_hi:[1,0]
	v_cvt_pk_bf16_f32 v4, v4, v5
	v_cvt_pk_bf16_f32 v5, v6, v7
	v_pk_mul_f32 v[6:7], v[26:27], v[34:35] op_sel_hi:[1,0]
	v_pk_mul_f32 v[8:9], v[28:29], v[34:35] op_sel_hi:[1,0]
	v_cvt_pk_bf16_f32 v6, v6, v7
	v_cvt_pk_bf16_f32 v7, v8, v9
	v_pk_mul_f32 v[8:9], v[30:31], v[34:35] op_sel_hi:[1,0]
	v_permlane32_swap_b32_e32 v2, v4
	v_cvt_pk_bf16_f32 v8, v8, v9
	v_cvt_pk_bf16_f32 v9, v10, v11
	v_permlane32_swap_b32_e32 v3, v5
	v_permlane32_swap_b32_e32 v6, v8
	v_permlane32_swap_b32_e32 v7, v9
	global_store_dwordx4 v[36:37], v[2:5], off offset:64
	global_store_dwordx4 v[36:37], v[6:9], off offset:96
	ds_read_b128 v[118:121], v219
	ds_read_b128 v[122:125], v219 offset:32
	ds_read_b128 v[126:129], v219 offset:64
	ds_read_b128 v[130:133], v219 offset:13856
	ds_read_b128 v[134:137], v219 offset:96
	ds_read_b128 v[138:141], v219 offset:4608
	s_waitcnt lgkmcnt(5)
	v_mfma_f32_32x32x16_bf16 v[18:33], v[118:121], v[94:97], 0
	ds_read_b128 v[118:121], v219 offset:4640
	s_waitcnt lgkmcnt(5)
	v_mfma_f32_32x32x16_bf16 v[18:33], v[122:125], v[90:93], v[18:33]
	ds_read_b128 v[122:125], v219 offset:4672
	s_waitcnt lgkmcnt(5)
	v_mfma_f32_32x32x16_bf16 v[18:33], v[126:129], v[86:89], v[18:33]
	ds_read_b128 v[126:129], v219 offset:4704
	s_waitcnt lgkmcnt(4)
	v_mfma_f32_32x32x16_bf16 v[18:33], v[134:137], v[82:85], v[18:33]
	ds_read_b128 v[134:137], v219 offset:9216
	s_waitcnt lgkmcnt(4)
	v_mfma_f32_32x32x16_bf16 v[34:49], v[138:141], v[94:97], 0
	ds_read_b128 v[138:141], v219 offset:9248
	s_waitcnt lgkmcnt(4)
	v_mfma_f32_32x32x16_bf16 v[34:49], v[118:121], v[90:93], v[34:49]
	ds_read_b128 v[118:121], v219 offset:9280
	s_waitcnt lgkmcnt(4)
	v_mfma_f32_32x32x16_bf16 v[34:49], v[122:125], v[86:89], v[34:49]
	ds_read_b128 v[122:125], v219 offset:9312
	s_waitcnt lgkmcnt(4)
	v_mfma_f32_32x32x16_bf16 v[34:49], v[126:129], v[82:85], v[34:49]
	ds_read_b128 v[126:129], v219 offset:13824
	s_waitcnt lgkmcnt(4)
	v_mfma_f32_32x32x16_bf16 v[50:65], v[134:137], v[94:97], 0
	ds_read_b128 v[134:137], v219 offset:13888
	s_waitcnt lgkmcnt(4)
	v_mfma_f32_32x32x16_bf16 v[50:65], v[138:141], v[90:93], v[50:65]
	ds_read_b128 v[138:141], v219 offset:13920
	s_waitcnt lgkmcnt(4)
	v_mfma_f32_32x32x16_bf16 v[50:65], v[118:121], v[86:89], v[50:65]
	ds_read_b128 v[118:121], v219 offset:18432
	s_waitcnt lgkmcnt(4)
	v_mfma_f32_32x32x16_bf16 v[50:65], v[122:125], v[82:85], v[50:65]
	ds_read_b128 v[122:125], v219 offset:18464
	s_waitcnt lgkmcnt(4)
	v_mfma_f32_32x32x16_bf16 v[2:17], v[126:129], v[94:97], 0
	ds_read_b128 v[126:129], v219 offset:18496
	v_mfma_f32_32x32x16_bf16 v[2:17], v[130:133], v[90:93], v[2:17]
	ds_read_b128 v[130:133], v219 offset:18528
	s_waitcnt lgkmcnt(5)
	v_mfma_f32_32x32x16_bf16 v[2:17], v[134:137], v[86:89], v[2:17]
	s_waitcnt lgkmcnt(4)
	v_mfma_f32_32x32x16_bf16 v[2:17], v[138:141], v[82:85], v[2:17]
	s_waitcnt lgkmcnt(3)
	v_mfma_f32_32x32x16_bf16 v[66:81], v[118:121], v[94:97], 0
	s_waitcnt lgkmcnt(2)
	v_mfma_f32_32x32x16_bf16 v[66:81], v[122:125], v[90:93], v[66:81]
	s_waitcnt lgkmcnt(1)
	v_mfma_f32_32x32x16_bf16 v[66:81], v[126:129], v[86:89], v[66:81]
	s_waitcnt lgkmcnt(0)
	v_mfma_f32_32x32x16_bf16 v[66:81], v[130:133], v[82:85], v[66:81]
	s_cbranch_vccnz .LBB0_530
	v_readlane_b32 s0, v255, 17
	v_readlane_b32 s1, v255, 18
	s_nop 1
	v_cndmask_b32_e64 v82, v248, v18, s[0:1]
	v_readlane_b32 s0, v255, 19
	v_readlane_b32 s1, v255, 20
	s_nop 1
	v_cndmask_b32_e64 v83, v248, v19, s[0:1]
	v_readlane_b32 s0, v255, 21
	v_readlane_b32 s1, v255, 22
	s_nop 1
	v_cndmask_b32_e64 v18, v248, v20, s[0:1]
	v_readlane_b32 s0, v255, 37
	v_readlane_b32 s1, v255, 38
	s_nop 1
	v_cndmask_b32_e64 v19, v248, v21, s[0:1]
	v_readlane_b32 s0, v255, 39
	v_readlane_b32 s1, v255, 40
	s_nop 1
	v_cndmask_b32_e64 v21, v248, v22, s[0:1]
	v_readlane_b32 s0, v255, 41
	v_readlane_b32 s1, v255, 42
	s_nop 1
	v_cndmask_b32_e64 v84, v248, v23, s[0:1]
	v_readlane_b32 s0, v255, 43
	v_readlane_b32 s1, v255, 44
	s_nop 1
	v_cndmask_b32_e64 v20, v248, v24, s[0:1]
	v_readlane_b32 s0, v255, 45
	v_readlane_b32 s1, v255, 46
	s_nop 1
	v_cndmask_b32_e64 v22, v248, v25, s[0:1]
	v_readlane_b32 s0, v255, 47
	v_readlane_b32 s1, v255, 48
	s_nop 1
	v_cndmask_b32_e64 v24, v248, v26, s[0:1]
	v_readlane_b32 s0, v255, 49
	v_readlane_b32 s1, v255, 50
	s_nop 1
	v_cndmask_b32_e64 v27, v248, v27, s[0:1]
	v_readlane_b32 s0, v255, 51
	v_readlane_b32 s1, v255, 52
	s_nop 1
	v_cndmask_b32_e64 v23, v248, v28, s[0:1]
	v_readlane_b32 s0, v255, 53
	v_readlane_b32 s1, v255, 54
	s_nop 1
	v_cndmask_b32_e64 v25, v248, v29, s[0:1]
	v_readlane_b32 s0, v255, 55
	v_readlane_b32 s1, v255, 56
	s_nop 1
	v_cndmask_b32_e64 v28, v248, v30, s[0:1]
	v_readlane_b32 s0, v255, 57
	v_readlane_b32 s1, v255, 58
	s_nop 1
	v_cndmask_b32_e64 v30, v248, v31, s[0:1]
	v_readlane_b32 s0, v255, 59
	v_readlane_b32 s1, v255, 60
	s_nop 1
	v_cndmask_b32_e64 v26, v248, v32, s[0:1]
	v_readlane_b32 s0, v255, 61
	v_readlane_b32 s1, v255, 62
	s_nop 1
	v_cndmask_b32_e64 v29, v248, v33, s[0:1]
	s_branch .LBB0_531

; #define LAS __attribute__((address_space(3)))
; __device__ __forceinline__ __amdgpu_buffer_rsrc_t bsrc(const void* p) { return __builtin_amdgcn_make_buffer_rsrc((void*)p, (short)0, 0x7fffffff, 0x00020000); }
; __device__ __forceinline__ u32x4 bld16s(const __amdgpu_buffer_rsrc_t r, const unsigned lane_off, const unsigned scalar_off) { return __builtin_bit_cast(u32x4, __builtin_amdgcn_raw_buffer_load_b128(r, lane_off, scalar_off, 0)); }
; __device__ __forceinline__ void mixers_phase(Frame& F, const Args& a, int l, const bool do_conv) {
;     ...
;                 {
;                     f32x16 acc = {};
;                     const LAS unsigned char* ap = ux + (rb * 32 + l31) * UX_PITCH + hi * 16;
; #pragma unroll
;                     for (int ks = 0; ks < 16; ++ks) acc = __builtin_amdgcn_mfma_f32_32x32x16_bf16(*(const LAS bf16x8*)(ap + ks * 32), gfr[ks], acc, 0, 0, 0);
; #pragma unroll
;                     for (int r = 0; r < 16; ++r) S[(rb * 32 + (r & 3) + 8 * (r >> 2) + 4 * hi) * 128 + cb * 32 + l31] = acc[r];
;                 }
;                 bf16x8 afr[24];
;                 const int rbk = (wave < 4) ? wave : 11 - wave;
;                 { const __amdgpu_buffer_rsrc_t rw_ = bsrc(wy); const unsigned lo_ = (unsigned)lane * 16u, so_ = (unsigned)rbk * 24u * 1024u;
; #pragma unroll
;                   for (int ks = 0; ks < 24; ++ks) if (ks >= 16 || ks <= 2 * rbk + 1) afr[ks] = __builtin_bit_cast(bf16x8, bld16s(rw_, lo_, so_ + (unsigned)ks * 1024u)); else afr[ks] = (bf16x8){0, 0, 0, 0, 0, 0, 0, 0}; }
.LBB0_534:
	s_waitcnt lgkmcnt(0)
	s_barrier
	ds_read_b128 v[118:121], v230
	ds_read_b128 v[122:125], v230 offset:32
	ds_read_b128 v[126:129], v230 offset:64
	ds_read_b128 v[130:133], v230 offset:96
	ds_read_b128 v[134:137], v230 offset:128
	ds_read_b128 v[138:141], v230 offset:160
	v_readlane_b32 s2, v252, 6
	v_readlane_b32 s3, v252, 7
	s_andn2_b64 vcc, exec, s[2:3]
	s_waitcnt vmcnt(15)
	s_waitcnt lgkmcnt(5)
	v_mfma_f32_32x32x16_bf16 v[2:17], v[118:121], v[2:5], 0
	ds_read_b128 v[118:121], v230 offset:192
	v_cndmask_b32_e64 v0, 0, 1, s[2:3]
	v_cmp_ne_u32_e64 s[26:27], 1, v0
	s_waitcnt vmcnt(14)
	s_waitcnt lgkmcnt(5)
	v_mfma_f32_32x32x16_bf16 v[2:17], v[122:125], v[86:89], v[2:17]
	s_waitcnt vmcnt(13)
	ds_read_b128 v[122:125], v230 offset:224
	s_waitcnt lgkmcnt(5)
	v_mfma_f32_32x32x16_bf16 v[2:17], v[126:129], v[90:93], v[2:17]
	s_waitcnt vmcnt(12)
	ds_read_b128 v[126:129], v230 offset:256
	s_waitcnt lgkmcnt(5)
	v_mfma_f32_32x32x16_bf16 v[2:17], v[130:133], v[78:81], v[2:17]
	s_waitcnt vmcnt(11)
	ds_read_b128 v[130:133], v230 offset:288
	s_waitcnt lgkmcnt(5)
	v_mfma_f32_32x32x16_bf16 v[2:17], v[134:137], v[82:85], v[2:17]
	s_waitcnt vmcnt(10)
	ds_read_b128 v[134:137], v230 offset:320
	s_waitcnt lgkmcnt(5)
	v_mfma_f32_32x32x16_bf16 v[2:17], v[138:141], v[70:73], v[2:17]
	s_waitcnt vmcnt(9)
	ds_read_b128 v[138:141], v230 offset:352
	s_waitcnt lgkmcnt(5)
	v_mfma_f32_32x32x16_bf16 v[2:17], v[118:121], v[74:77], v[2:17]
	s_waitcnt vmcnt(8)
	ds_read_b128 v[118:121], v230 offset:384
	s_waitcnt lgkmcnt(5)
	v_mfma_f32_32x32x16_bf16 v[2:17], v[122:125], v[62:65], v[2:17]
	s_waitcnt vmcnt(7)
	ds_read_b128 v[122:125], v230 offset:416
	s_waitcnt lgkmcnt(5)
	v_mfma_f32_32x32x16_bf16 v[2:17], v[126:129], v[66:69], v[2:17]
	s_waitcnt vmcnt(6)
	ds_read_b128 v[126:129], v230 offset:448
	s_waitcnt lgkmcnt(5)
	v_mfma_f32_32x32x16_bf16 v[2:17], v[130:133], v[54:57], v[2:17]
	s_waitcnt vmcnt(5)
	ds_read_b128 v[130:133], v230 offset:480
	s_waitcnt lgkmcnt(5)
	v_mfma_f32_32x32x16_bf16 v[2:17], v[134:137], v[58:61], v[2:17]
	s_waitcnt vmcnt(4)
	s_waitcnt lgkmcnt(4)
	v_mfma_f32_32x32x16_bf16 v[2:17], v[138:141], v[30:33], v[2:17]
	s_waitcnt vmcnt(3)
	s_waitcnt lgkmcnt(3)
	v_mfma_f32_32x32x16_bf16 v[2:17], v[118:121], v[50:53], v[2:17]
	s_waitcnt vmcnt(2)
	s_waitcnt lgkmcnt(2)
	v_mfma_f32_32x32x16_bf16 v[2:17], v[122:125], v[22:25], v[2:17]
	s_waitcnt vmcnt(1)
	s_waitcnt lgkmcnt(1)
	v_mfma_f32_32x32x16_bf16 v[2:17], v[126:129], v[26:29], v[2:17]
	s_waitcnt vmcnt(0)
	s_waitcnt lgkmcnt(0)
	v_mfma_f32_32x32x16_bf16 v[2:17], v[130:133], v[18:21], v[2:17]
	s_nop 11
	ds_write2st64_b32 v231, v2, v3 offset0:196 offset1:198
	ds_write2st64_b32 v231, v4, v5 offset0:200 offset1:202
	ds_write2st64_b32 v231, v6, v7 offset0:212 offset1:214
	ds_write2st64_b32 v231, v8, v9 offset0:216 offset1:218
	ds_write2st64_b32 v231, v10, v11 offset0:228 offset1:230
	ds_write2st64_b32 v231, v12, v13 offset0:232 offset1:234
	ds_write2st64_b32 v231, v14, v15 offset0:244 offset1:246
	ds_write2st64_b32 v231, v16, v17 offset0:248 offset1:250
	s_cbranch_vccnz .LBB0_537
	s_mov_b32 s74, s78
	s_mov_b32 s75, s79
	v_readlane_b32 s2, v252, 52
	s_nop 4
	buffer_load_dwordx4 v[2:5], v180, s[72:75], s2 offen
	s_and_b64 vcc, exec, s[26:27]
	s_cbranch_vccz .LBB0_538
